# conv halo fix-up done per workgroup for the two row tiles its out-projection reads; the two grid barriers behind it removed
# baseline (speedup 1.0000x reference)
; DI unsigned pk2(float lo, float hi) { return pg8::cvt_pk_bf16(lo, hi); }
; DI float bflo(unsigned u) { return __uint_as_float(u << 16); }
; DI float bfhi(unsigned u) { return __uint_as_float(u & 0xffff0000u); }
; DI int launder(int x) { asm volatile("" : "+v"(x)); return x; }
; DI void conv_fix_phase(const bf16* VB, const bf16* BGB, bf16* Y, const float* cw, const float* cb, int G, int blk) {
;     const int gtid = blk * NTHREADS + launder((int)threadIdx.x); const int stride = G * NTHREADS;
;     const int ch = (gtid & 255) * 8;
;     float w0[8], w1[8], w2[8], bb[8];
; #pragma unroll
;     for (int e = 0; e < 8; ++e) { w0[e] = cw[ch + e]; w1[e] = cw[2048 + ch + e]; w2[e] = cw[4096 + ch + e]; bb[e] = cb[ch + e]; }
;     for (int idx = gtid; idx < (M / 64) * 2 * 256; idx += stride) {
;         const int sj = idx >> 8, slab = sj >> 1, j = sj & 1;
;         const bool first = (slab & 31) == 0;
;         const u32x4 z = {0u, 0u, 0u, 0u};
;         const u32x4 v0 = *(const u32x4*)(VB + ((size_t)slab * 4 + 2 + j) * 2048 + ch);
;         const u32x4 v1 = j ? *(const u32x4*)(VB + ((size_t)slab * 4 + 2) * 2048 + ch) : (first ? z : *(const u32x4*)(VB + ((size_t)(slab - 1) * 4 + 1) * 2048 + ch));
;         const u32x4 v2 = first ? z : *(const u32x4*)(VB + ((size_t)(slab - 1) * 4 + j) * 2048 + ch);
;         const u32x4 bg = *(const u32x4*)(BGB + ((size_t)slab * 2 + j) * 2048 + ch);
;         u32x4 o;
; #pragma unroll
;         for (int p = 0; p < 4; ++p) {
;             const float c0 = bb[2 * p] + w0[2 * p] * bflo(v2[p]) + w1[2 * p] * bflo(v1[p]) + w2[2 * p] * bflo(v0[p]);
;             const float c1 = bb[2 * p + 1] + w0[2 * p + 1] * bfhi(v2[p]) + w1[2 * p + 1] * bfhi(v1[p]) + w2[2 * p + 1] * bfhi(v0[p]);
;             o[p] = pk2(bflo(bg[p]) * c0, bfhi(bg[p]) * c1);
;         }
;         *(u32x4*)(Y + ((size_t)slab * 64 + j) * 2048 + ch) = o;
;     }
; }
.LBB0_218:
	s_cmp_lt_i32 s90, 3
	s_cselect_b64 s[0:1], -1, 0
	s_and_b64 s[4:5], s[0:1], s[2:3]
	s_andn2_b64 vcc, exec, s[4:5]
	s_cbranch_vccnz .LBB0_233
	v_mov_b32_e32 v0, v196
	s_and_b32 s0, s89, 7
	s_lshl_b32 s0, s0, 4
	s_bfe_u32 vcc_lo, s89, 0x30003
	s_add_i32 s0, s0, vcc_lo
	s_lshl_b32 s0, s0, 11
	v_add_u32_e32 v45, s0, v0
	s_mov_b32 s0, 0x40000
	v_cmp_gt_i32_e32 vcc, s0, v45
	s_and_saveexec_b64 s[0:1], vcc
	s_cbranch_execz .LBB0_232
	v_readlane_b32 s8, v254, 35
	v_lshlrev_b32_e32 v0, 3, v0
	v_readlane_b32 s9, v254, 36
	v_readlane_b32 s10, v254, 37
	v_readlane_b32 s11, v254, 38
	v_readlane_b32 s12, v254, 39
	v_readlane_b32 s13, v254, 40
	v_readlane_b32 s14, v254, 41
	v_readlane_b32 s15, v254, 42
	v_and_b32_e32 v44, 0x7f8, v0
	v_readlane_b32 s16, v254, 43
	v_readlane_b32 s17, v254, 44
	v_readlane_b32 s18, v254, 45
	v_readlane_b32 s19, v254, 46
	s_mov_b64 s[8:9], s[12:13]
	v_mov_b32_e32 v47, 0
	v_lshlrev_b32_e32 v46, 2, v44
	s_mov_b64 s[10:11], s[14:15]
	v_lshl_add_u64 v[0:1], s[10:11], 0, v[46:47]
	s_mov_b64 s[2:3], 0x2000
	v_lshl_add_u64 v[8:9], v[0:1], 0, s[2:3]
	s_mov_b64 s[2:3], 0x4000
	v_lshl_add_u64 v[12:13], v[0:1], 0, s[2:3]
	s_movk_i32 s2, 0x2000
	v_add_co_u32_e32 v2, vcc, s2, v0
	s_movk_i32 s2, 0x4000
	s_nop 0
	v_addc_co_u32_e32 v3, vcc, 0, v1, vcc
	v_add_co_u32_e32 v4, vcc, s2, v0
	s_mov_b64 s[12:13], s[16:17]
	s_nop 0
	v_addc_co_u32_e32 v5, vcc, 0, v1, vcc
	global_load_dwordx4 v[0:3], v[2:3], off
	s_nop 0
	global_load_dwordx4 v[4:7], v[4:5], off
	s_nop 0
	global_load_dwordx4 v[8:11], v[8:9], off offset:16
	s_waitcnt lgkmcnt(0)
	global_load_dwordx4 v[12:15], v[12:13], off offset:16
	s_nop 0
	global_load_dwordx4 v[16:19], v46, s[10:11] offset:16
	global_load_dwordx4 v[20:23], v46, s[12:13] offset:16
	global_load_dwordx4 v[24:27], v46, s[10:11]
	global_load_dwordx4 v[28:31], v46, s[12:13]
	v_lshlrev_b32_e32 v46, 1, v44
	s_mov_b64 s[14:15], s[18:19]
	s_movk_i32 s12, 0x200
	v_lshl_add_u64 v[48:49], s[70:71], 0, v[46:47]
	s_mov_b64 s[6:7], 0
	s_mov_b32 s13, 0
	v_readlane_b32 s20, v254, 47
	v_readlane_b32 s21, v254, 48
	v_readlane_b32 s22, v254, 49
	v_readlane_b32 s23, v254, 50
	s_branch .LBB0_222
.LBB0_221:
	s_or_b64 exec, exec, s[2:3]
	v_lshlrev_b64 v[54:55], 13, v[50:51]
	v_lshl_add_u64 v[54:55], s[62:63], 0, v[54:55]
	v_lshl_add_u64 v[54:55], v[54:55], 0, v[52:53]
	v_lshl_add_u64 v[54:55], v[54:55], 0, v[46:47]
	global_load_dwordx4 v[54:57], v[54:55], off
	s_waitcnt vmcnt(1)
	v_lshlrev_b32_e32 v58, 16, v40
	v_and_b32_e32 v59, 0xffff0000, v40
	v_lshlrev_b32_e32 v40, 16, v41
	v_and_b32_e32 v41, 0xffff0000, v41
	v_lshlrev_b32_e32 v64, 16, v42
	v_and_b32_e32 v65, 0xffff0000, v42
	v_lshlrev_b32_e32 v42, 16, v43
	v_and_b32_e32 v43, 0xffff0000, v43
	v_lshlrev_b64 v[50:51], 18, v[50:51]
	v_lshlrev_b32_e32 v60, 16, v36
	v_and_b32_e32 v61, 0xffff0000, v36
	v_lshlrev_b32_e32 v36, 16, v37
	v_and_b32_e32 v37, 0xffff0000, v37
	v_lshlrev_b32_e32 v66, 16, v38
	v_and_b32_e32 v67, 0xffff0000, v38
	v_lshlrev_b32_e32 v38, 16, v39
	v_and_b32_e32 v39, 0xffff0000, v39
	v_pk_fma_f32 v[58:59], v[24:25], v[58:59], v[28:29]
	v_pk_fma_f32 v[40:41], v[26:27], v[40:41], v[30:31]
	v_pk_fma_f32 v[64:65], v[16:17], v[64:65], v[20:21]
	v_pk_fma_f32 v[42:43], v[18:19], v[42:43], v[22:23]
	v_lshl_add_u64 v[50:51], s[60:61], 0, v[50:51]
	v_lshlrev_b32_e32 v62, 16, v32
	v_and_b32_e32 v63, 0xffff0000, v32
	v_lshlrev_b32_e32 v32, 16, v33
	v_and_b32_e32 v33, 0xffff0000, v33
	v_lshlrev_b32_e32 v68, 16, v34
	v_and_b32_e32 v69, 0xffff0000, v34
	v_lshlrev_b32_e32 v34, 16, v35
	v_and_b32_e32 v35, 0xffff0000, v35
	v_pk_fma_f32 v[58:59], v[0:1], v[60:61], v[58:59]
	v_pk_fma_f32 v[36:37], v[2:3], v[36:37], v[40:41]
	v_pk_fma_f32 v[40:41], v[8:9], v[66:67], v[64:65]
	v_pk_fma_f32 v[38:39], v[10:11], v[38:39], v[42:43]
	v_lshl_add_u64 v[42:43], v[50:51], 0, v[52:53]
	s_add_i32 s13, s13, 1
	s_movk_i32 s12, 0x200
	s_cmp_eq_u32 s13, 4
	s_cselect_b32 s12, 0x3a00, s12
	v_add_u32_e32 v45, s12, v45
	v_pk_fma_f32 v[50:51], v[4:5], v[62:63], v[58:59]
	v_pk_fma_f32 v[32:33], v[6:7], v[32:33], v[36:37]
	v_pk_fma_f32 v[36:37], v[12:13], v[68:69], v[40:41]
	v_pk_fma_f32 v[34:35], v[14:15], v[34:35], v[38:39]
	v_lshl_add_u64 v[38:39], v[42:43], 0, v[46:47]
	s_cmp_ge_u32 s13, 8
	s_cselect_b64 s[6:7], exec, 0
	s_waitcnt vmcnt(0)
	v_lshlrev_b32_e32 v40, 16, v54
	v_and_b32_e32 v41, 0xffff0000, v54
	v_lshlrev_b32_e32 v42, 16, v55
	v_and_b32_e32 v43, 0xffff0000, v55
	v_lshlrev_b32_e32 v52, 16, v56
	v_and_b32_e32 v53, 0xffff0000, v56
	v_lshlrev_b32_e32 v54, 16, v57
	v_and_b32_e32 v55, 0xffff0000, v57
	v_pk_mul_f32 v[40:41], v[50:51], v[40:41]
	v_pk_mul_f32 v[42:43], v[32:33], v[42:43]
	v_pk_mul_f32 v[36:37], v[36:37], v[52:53]
	v_pk_mul_f32 v[50:51], v[34:35], v[54:55]
	v_cvt_pk_bf16_f32 v32, v40, v41
	v_cvt_pk_bf16_f32 v33, v42, v43
	v_cvt_pk_bf16_f32 v34, v36, v37
	v_cvt_pk_bf16_f32 v35, v50, v51
	global_store_dwordx4 v[38:39], v[32:35], off
	s_andn2_b64 exec, exec, s[6:7]
	s_cbranch_execz .LBB0_232

; __device__ __forceinline__ unsigned xb_ld(unsigned* p)              { return __hip_atomic_load(p, __ATOMIC_RELAXED, __HIP_MEMORY_SCOPE_AGENT); }
; __device__ __forceinline__ unsigned xb_add(unsigned* p, unsigned v) { return __hip_atomic_fetch_add(p, v, __ATOMIC_RELAXED, __HIP_MEMORY_SCOPE_AGENT); }
; #define XB_SPIN(cond, bar) do { unsigned _sp = 0; while (cond) { __builtin_amdgcn_s_sleep(1); \
;     if ((++_sp & 255u) == 0u) { if (xb_ld(&(bar)[XB_TMO])) break; if (_sp > XB_SPIN_CAP) { atomicAdd(&(bar)[XB_TMO], 1u); break; } } } } while (0)
; __device__ __forceinline__ void xcd_barrier(const XcdBarrier& b) {
;     asm volatile("s_waitcnt vmcnt(0)" ::: "memory");
;     __syncthreads();
;     if (threadIdx.x == 0) {
;         unsigned* bar = b.bar;
;         __builtin_amdgcn_s_waitcnt(0);
;         unsigned nloc = b.st[0], nx = b.st[1];
;         if (nloc == 0u) { xcd_barrier_complete(bar, b.x, nloc, nx); b.st[0] = nloc; b.st[1] = nx; }
;         const unsigned old = xb_add(&bar[XB_XSUB(b.x)], 1u);
;         const unsigned gen = old / nloc;
;         if (old + 1u == (gen + 1u) * nloc) {
;             __builtin_amdgcn_fence(__ATOMIC_RELEASE, "agent");
;             asm volatile("s_waitcnt vmcnt(0)" ::: "memory");
;             const unsigned og = xb_add(&bar[XB_TOP], 1u);
;             const unsigned tg = og / nx;
;             if (og + 1u == (tg + 1u) * nx) xb_add(&bar[XB_TOPGEN], 1u);
;             else XB_SPIN(xb_ld(&bar[XB_TOPGEN]) == tg, bar);
;             __builtin_amdgcn_fence(__ATOMIC_ACQUIRE, "agent");
;             xb_add(&bar[XB_XGEN(b.x)], 1u);
;             asm volatile("s_waitcnt vmcnt(0)" ::: "memory");
;         } else {
;             XB_SPIN(xb_ld(&bar[XB_XGEN(b.x)]) == gen, bar);
;             __builtin_amdgcn_fence(__ATOMIC_ACQUIRE, "agent");
;             asm volatile("s_waitcnt vmcnt(0)" ::: "memory");
;         }
;     }
;     __syncthreads();
; }
.LBB0_233:
	s_cmp_gt_i32 s91, 3
	s_cselect_b64 s[0:1], -1, 0
	s_and_b64 s[2:3], s[4:5], s[0:1]
	s_andn2_b64 vcc, exec, s[2:3]
	s_mov_b32 s36, s74
	s_cbranch_vccnz .LBB0_287
	s_waitcnt vmcnt(0)
	s_barrier

; DI unsigned pk2(float lo, float hi) { return pg8::cvt_pk_bf16(lo, hi); }
; DI float bflo(unsigned u) { return __uint_as_float(u << 16); }
; DI float bfhi(unsigned u) { return __uint_as_float(u & 0xffff0000u); }
; DI int launder(int x) { asm volatile("" : "+v"(x)); return x; }
; DI void conv_fix_phase(const bf16* VB, const bf16* BGB, bf16* Y, const float* cw, const float* cb, int G, int blk) {
;     const int gtid = blk * NTHREADS + launder((int)threadIdx.x); const int stride = G * NTHREADS;
;     const int ch = (gtid & 255) * 8;
;     float w0[8], w1[8], w2[8], bb[8];
; #pragma unroll
;     for (int e = 0; e < 8; ++e) { w0[e] = cw[ch + e]; w1[e] = cw[2048 + ch + e]; w2[e] = cw[4096 + ch + e]; bb[e] = cb[ch + e]; }
;     for (int idx = gtid; idx < (M / 64) * 2 * 256; idx += stride) {
;         const int sj = idx >> 8, slab = sj >> 1, j = sj & 1;
;         const bool first = (slab & 31) == 0;
;         const u32x4 z = {0u, 0u, 0u, 0u};
;         const u32x4 v0 = *(const u32x4*)(VB + ((size_t)slab * 4 + 2 + j) * 2048 + ch);
;         const u32x4 v1 = j ? *(const u32x4*)(VB + ((size_t)slab * 4 + 2) * 2048 + ch) : (first ? z : *(const u32x4*)(VB + ((size_t)(slab - 1) * 4 + 1) * 2048 + ch));
;         const u32x4 v2 = first ? z : *(const u32x4*)(VB + ((size_t)(slab - 1) * 4 + j) * 2048 + ch);
;         const u32x4 bg = *(const u32x4*)(BGB + ((size_t)slab * 2 + j) * 2048 + ch);
;         u32x4 o;
; #pragma unroll
;         for (int p = 0; p < 4; ++p) {
;             const float c0 = bb[2 * p] + w0[2 * p] * bflo(v2[p]) + w1[2 * p] * bflo(v1[p]) + w2[2 * p] * bflo(v0[p]);
;             const float c1 = bb[2 * p + 1] + w0[2 * p + 1] * bfhi(v2[p]) + w1[2 * p + 1] * bfhi(v1[p]) + w2[2 * p + 1] * bfhi(v0[p]);
;             o[p] = pk2(bflo(bg[p]) * c0, bfhi(bg[p]) * c1);
;         }
;         *(u32x4*)(Y + ((size_t)slab * 64 + j) * 2048 + ch) = o;
;     }
; }
.LBB0_1462:
	s_cmp_lt_i32 s90, 16
	s_cselect_b64 s[0:1], -1, 0
	s_and_b64 s[4:5], s[0:1], s[2:3]
	s_andn2_b64 vcc, exec, s[4:5]
	s_cbranch_vccnz .LBB0_1477
	v_mov_b32_e32 v0, v196
	s_and_b32 s0, s89, 7
	s_lshl_b32 s0, s0, 4
	s_bfe_u32 vcc_lo, s89, 0x30003
	s_add_i32 s0, s0, vcc_lo
	s_lshl_b32 s0, s0, 11
	v_add_u32_e32 v45, s0, v0
	s_mov_b32 s0, 0x40000
	v_cmp_gt_i32_e32 vcc, s0, v45
	s_and_saveexec_b64 s[0:1], vcc
	s_cbranch_execz .LBB0_1476
	v_lshlrev_b32_e32 v0, 3, v0
	v_readlane_b32 s8, v254, 35
	v_and_b32_e32 v44, 0x7f8, v0
	v_readlane_b32 s14, v254, 41
	v_readlane_b32 s15, v254, 42
	v_mov_b32_e32 v47, 0
	v_lshlrev_b32_e32 v46, 2, v44
	s_mov_b64 s[6:7], s[14:15]
	v_lshl_add_u64 v[16:17], s[6:7], 0, v[46:47]
	s_mov_b64 s[2:3], 0x6000
	v_readlane_b32 s9, v254, 36
	v_readlane_b32 s16, v254, 43
	v_readlane_b32 s17, v254, 44
	v_lshl_add_u64 v[18:19], v[16:17], 0, s[2:3]
	s_mov_b64 s[2:3], 0x8000
	s_mov_b64 s[8:9], s[16:17]
	v_lshl_add_u64 v[20:21], v[16:17], 0, s[2:3]
	s_mov_b64 s[2:3], 0xa000
	v_lshl_add_u64 v[24:25], v[16:17], 0, s[2:3]
	v_lshl_add_u64 v[26:27], s[8:9], 0, v[46:47]
	s_mov_b64 s[2:3], 0x2000
	v_lshl_add_u64 v[32:33], v[26:27], 0, s[2:3]
	s_movk_i32 s2, 0x6000
	v_add_co_u32_e32 v22, vcc, s2, v16
	s_mov_b32 s2, 0x8000
	s_nop 0
	v_addc_co_u32_e32 v23, vcc, 0, v17, vcc
	v_add_co_u32_e32 v28, vcc, s2, v16
	s_mov_b32 s2, 0xa000
	s_nop 0
	v_addc_co_u32_e32 v29, vcc, 0, v17, vcc
	s_waitcnt lgkmcnt(0)
	global_load_dwordx4 v[0:3], v[22:23], off
	global_load_dwordx4 v[4:7], v[28:29], off
	global_load_dwordx4 v[8:11], v[18:19], off offset:16
	global_load_dwordx4 v[12:15], v[20:21], off offset:16
	v_add_co_u32_e32 v28, vcc, s2, v16
	s_movk_i32 s2, 0x2000
	s_nop 0
	v_addc_co_u32_e32 v29, vcc, 0, v17, vcc
	v_add_co_u32_e32 v34, vcc, s2, v26
	global_load_dwordx4 v[16:19], v[28:29], off
	global_load_dwordx4 v[20:23], v[24:25], off offset:16
	v_addc_co_u32_e32 v35, vcc, 0, v27, vcc
	global_load_dwordx4 v[24:27], v[34:35], off
	global_load_dwordx4 v[28:31], v[32:33], off offset:16
	v_readlane_b32 s12, v254, 39
	v_readlane_b32 s13, v254, 40
	v_lshlrev_b32_e32 v46, 1, v44
	s_movk_i32 s12, 0x200
	v_lshl_add_u64 v[48:49], s[70:71], 0, v[46:47]
	s_mov_b64 s[6:7], 0
	s_mov_b32 s13, 0
	v_readlane_b32 s10, v254, 37
	v_readlane_b32 s11, v254, 38
	v_readlane_b32 s18, v254, 45
	v_readlane_b32 s19, v254, 46
	v_readlane_b32 s20, v254, 47
	v_readlane_b32 s21, v254, 48
	v_readlane_b32 s22, v254, 49
	v_readlane_b32 s23, v254, 50
	s_branch .LBB0_1466
.LBB0_1465:
	s_or_b64 exec, exec, s[2:3]
	v_lshlrev_b64 v[54:55], 13, v[50:51]
	v_lshl_add_u64 v[54:55], s[62:63], 0, v[54:55]
	v_lshl_add_u64 v[54:55], v[54:55], 0, v[52:53]
	v_lshl_add_u64 v[54:55], v[54:55], 0, v[46:47]
	global_load_dwordx4 v[54:57], v[54:55], off
	s_waitcnt vmcnt(0)
	v_lshlrev_b32_e32 v58, 16, v40
	v_and_b32_e32 v59, 0xffff0000, v40
	v_lshlrev_b32_e32 v40, 16, v41
	v_and_b32_e32 v41, 0xffff0000, v41
	v_lshlrev_b32_e32 v64, 16, v42
	v_and_b32_e32 v65, 0xffff0000, v42
	v_lshlrev_b32_e32 v42, 16, v43
	v_and_b32_e32 v43, 0xffff0000, v43
	v_lshlrev_b64 v[50:51], 18, v[50:51]
	v_lshlrev_b32_e32 v60, 16, v36
	v_and_b32_e32 v61, 0xffff0000, v36
	v_lshlrev_b32_e32 v36, 16, v37
	v_and_b32_e32 v37, 0xffff0000, v37
	v_lshlrev_b32_e32 v66, 16, v38
	v_and_b32_e32 v67, 0xffff0000, v38
	v_lshlrev_b32_e32 v38, 16, v39
	v_and_b32_e32 v39, 0xffff0000, v39
	v_pk_fma_f32 v[58:59], v[0:1], v[58:59], v[24:25]
	v_pk_fma_f32 v[40:41], v[2:3], v[40:41], v[26:27]
	v_pk_fma_f32 v[64:65], v[8:9], v[64:65], v[28:29]
	v_pk_fma_f32 v[42:43], v[10:11], v[42:43], v[30:31]
	v_lshl_add_u64 v[50:51], s[60:61], 0, v[50:51]
	v_lshlrev_b32_e32 v62, 16, v32
	v_and_b32_e32 v63, 0xffff0000, v32
	v_lshlrev_b32_e32 v32, 16, v33
	v_and_b32_e32 v33, 0xffff0000, v33
	v_lshlrev_b32_e32 v68, 16, v34
	v_and_b32_e32 v69, 0xffff0000, v34
	v_lshlrev_b32_e32 v34, 16, v35
	v_and_b32_e32 v35, 0xffff0000, v35
	v_pk_fma_f32 v[58:59], v[4:5], v[60:61], v[58:59]
	v_pk_fma_f32 v[36:37], v[6:7], v[36:37], v[40:41]
	v_pk_fma_f32 v[40:41], v[12:13], v[66:67], v[64:65]
	v_pk_fma_f32 v[38:39], v[14:15], v[38:39], v[42:43]
	v_lshl_add_u64 v[42:43], v[50:51], 0, v[52:53]
	s_add_i32 s13, s13, 1
	s_movk_i32 s12, 0x200
	s_cmp_eq_u32 s13, 4
	s_cselect_b32 s12, 0x3a00, s12
	v_add_u32_e32 v45, s12, v45
	v_pk_fma_f32 v[50:51], v[16:17], v[62:63], v[58:59]
	v_pk_fma_f32 v[32:33], v[18:19], v[32:33], v[36:37]
	v_pk_fma_f32 v[36:37], v[20:21], v[68:69], v[40:41]
	v_pk_fma_f32 v[34:35], v[22:23], v[34:35], v[38:39]
	v_lshl_add_u64 v[38:39], v[42:43], 0, v[46:47]
	s_cmp_ge_u32 s13, 8
	s_cselect_b64 s[6:7], exec, 0
	v_lshlrev_b32_e32 v40, 16, v54
	v_and_b32_e32 v41, 0xffff0000, v54
	v_lshlrev_b32_e32 v42, 16, v55
	v_and_b32_e32 v43, 0xffff0000, v55
	v_lshlrev_b32_e32 v52, 16, v56
	v_and_b32_e32 v53, 0xffff0000, v56
	v_lshlrev_b32_e32 v54, 16, v57
	v_and_b32_e32 v55, 0xffff0000, v57
	v_pk_mul_f32 v[40:41], v[50:51], v[40:41]
	v_pk_mul_f32 v[42:43], v[32:33], v[42:43]
	v_pk_mul_f32 v[36:37], v[36:37], v[52:53]
	v_pk_mul_f32 v[50:51], v[34:35], v[54:55]
	v_cvt_pk_bf16_f32 v32, v40, v41
	v_cvt_pk_bf16_f32 v33, v42, v43
	v_cvt_pk_bf16_f32 v34, v36, v37
	v_cvt_pk_bf16_f32 v35, v50, v51
	global_store_dwordx4 v[38:39], v[32:35], off
	s_andn2_b64 exec, exec, s[6:7]
	s_cbranch_execz .LBB0_1476

; __device__ __forceinline__ unsigned xb_ld(unsigned* p)              { return __hip_atomic_load(p, __ATOMIC_RELAXED, __HIP_MEMORY_SCOPE_AGENT); }
; __device__ __forceinline__ unsigned xb_add(unsigned* p, unsigned v) { return __hip_atomic_fetch_add(p, v, __ATOMIC_RELAXED, __HIP_MEMORY_SCOPE_AGENT); }
; #define XB_SPIN(cond, bar) do { unsigned _sp = 0; while (cond) { __builtin_amdgcn_s_sleep(1); \
;     if ((++_sp & 255u) == 0u) { if (xb_ld(&(bar)[XB_TMO])) break; if (_sp > XB_SPIN_CAP) { atomicAdd(&(bar)[XB_TMO], 1u); break; } } } } while (0)
; __device__ __forceinline__ void xcd_barrier(const XcdBarrier& b) {
;     asm volatile("s_waitcnt vmcnt(0)" ::: "memory");
;     __syncthreads();
;     if (threadIdx.x == 0) {
;         unsigned* bar = b.bar;
;         __builtin_amdgcn_s_waitcnt(0);
;         unsigned nloc = b.st[0], nx = b.st[1];
;         if (nloc == 0u) { xcd_barrier_complete(bar, b.x, nloc, nx); b.st[0] = nloc; b.st[1] = nx; }
;         const unsigned old = xb_add(&bar[XB_XSUB(b.x)], 1u);
;         const unsigned gen = old / nloc;
;         if (old + 1u == (gen + 1u) * nloc) {
;             __builtin_amdgcn_fence(__ATOMIC_RELEASE, "agent");
;             asm volatile("s_waitcnt vmcnt(0)" ::: "memory");
;             const unsigned og = xb_add(&bar[XB_TOP], 1u);
;             const unsigned tg = og / nx;
;             if (og + 1u == (tg + 1u) * nx) xb_add(&bar[XB_TOPGEN], 1u);
;             else XB_SPIN(xb_ld(&bar[XB_TOPGEN]) == tg, bar);
;             __builtin_amdgcn_fence(__ATOMIC_ACQUIRE, "agent");
;             xb_add(&bar[XB_XGEN(b.x)], 1u);
;             asm volatile("s_waitcnt vmcnt(0)" ::: "memory");
;         } else {
;             XB_SPIN(xb_ld(&bar[XB_XGEN(b.x)]) == gen, bar);
;             __builtin_amdgcn_fence(__ATOMIC_ACQUIRE, "agent");
;             asm volatile("s_waitcnt vmcnt(0)" ::: "memory");
;         }
;     }
;     __syncthreads();
; }
.LBB0_1477:
	s_cmp_gt_i32 s91, 16
	s_cselect_b64 s[0:1], -1, 0
	s_and_b64 s[2:3], s[4:5], s[0:1]
	s_andn2_b64 vcc, exec, s[2:3]
	s_cbranch_vccnz .LBB0_1531
	s_waitcnt vmcnt(0)
	s_barrier
